# block top-k selection rewritten: 8 queries per wave in one transposed pass (VALU counts + DPP group sums, bitmap words built per lane, no LDS atomics)
# speedup vs baseline: 1.0233x; 1.0233x over previous
; #define LAS __attribute__((address_space(3)))
; __device__ __forceinline__ void select_blocks(const LAS float* sc, LAS unsigned* selm, int jhi, int f1, int f2, int lane) {
;     unsigned key[4]; bool cand[4];
; #pragma unroll
;     for (int rr = 0; rr < 4; ++rr) { const int j = 4 * lane + rr; cand[rr] = (j >= 1) && (j <= jhi); key[rr] = cand[rr] ? __builtin_bit_cast(unsigned, sc[j]) : 0u; }
;     unsigned prefix = 0u;
; #pragma unroll 1
;     ...
;         const unsigned c = prefix | (1u << bit); int cnt = 0;
; #pragma unroll
;         for (int rr = 0; rr < 4; ++rr) cnt += __popcll(__ballot(cand[rr] && key[rr] >= c));
;         if (cnt >= 13) prefix = c;
; __device__ __forceinline__ void nsa_block_task(Ctx& C, int task, bf16* ONSA_OUT) {
;     ...
; #pragma unroll 1
;         for (int q = 0; q < 8; ++q) {
;             if (qb < 16) { if (lane < 8) SELM[q * 8 + lane] = (lane == 0) ? ((1u << (qb + 1)) - 1u) : 0u; }
;             else select_blocks(SC + q * 256, SELM + q * 8, qb - 2, qb, qb - 1, lane);
.LBB0_1152:
	s_cmp_gt_u32 s94, 15
	s_cselect_b64 s[34:35], -1, 0
	s_add_i32 s18, s94, -2
	s_add_i32 s0, s94, -1
	v_cmp_ge_i32_e32 vcc, s18, v193
	v_cmp_eq_u32_e64 s[30:31], s0, v224
	s_and_b64 s[36:37], s[6:7], vcc
	v_cmp_ge_i32_e32 vcc, s18, v223
	s_waitcnt vmcnt(0)
	v_cndmask_b32_e64 v52, 0, 8, s[30:31]
	s_lshl_b32 s30, 2, s94
	s_waitcnt lgkmcnt(0)
	s_and_b64 s[38:39], s[8:9], vcc
	v_cmp_ge_i32_e32 vcc, s18, v224
	s_add_i32 s30, s30, -1
	v_cmp_gt_u32_e64 s[16:17], s18, v193
	s_and_b64 s[40:41], s[8:9], vcc
	v_cmp_eq_u32_e32 vcc, s94, v193
	v_cmp_eq_u32_e64 s[18:19], s0, v193
	v_cmp_eq_u32_e64 s[24:25], s94, v222
	v_cmp_eq_u32_e64 s[20:21], s0, v222
	v_cmp_eq_u32_e64 s[26:27], s94, v223
	v_cmp_eq_u32_e64 s[22:23], s0, v223
	v_cmp_eq_u32_e64 s[28:29], s94, v224
	v_mov_b32_e32 v53, s30
	s_nor_b64 s[42:43], s[10:11], vcc
	v_cndmask_b32_e64 v0, 0, 1, s[18:19]
	v_cmp_ne_u32_e64 s[18:19], s94, v222
	s_mov_b32 s50, 0
	v_cndmask_b32_e64 v2, 0, 2, s[20:21]
	v_cmp_ne_u32_e64 s[20:21], s94, v223
	v_cndmask_b32_e64 v3, 0, 4, s[22:23]
	v_cmp_ne_u32_e64 s[22:23], s94, v224
	v_cndmask_b32_e64 v53, 0, v53, s[14:15]
	s_xor_b64 s[30:31], vcc, -1
	s_xor_b64 s[44:45], s[24:25], -1
	s_xor_b64 s[46:47], s[26:27], -1
	s_xor_b64 s[48:49], s[28:29], -1
	s_and_b64 vcc, exec, s[34:35]
	s_cbranch_vccz .Lselx_skip
	v_mbcnt_lo_u32_b32 v71, -1, 0
	v_mbcnt_hi_u32_b32 v71, -1, v71
	s_add_i32 s3, s94, -2
	v_lshl_add_u32 v72, v71, 7, s1
	ds_read_b128 v[148:151], v72
	ds_read_b128 v[152:155], v72 offset:16
	ds_read_b128 v[156:159], v72 offset:32
	ds_read_b128 v[160:163], v72 offset:48
	ds_read_b128 v[164:167], v72 offset:64
	ds_read_b128 v[168:171], v72 offset:80
	ds_read_b128 v[172:175], v72 offset:96
	ds_read_b128 v[176:179], v72 offset:112
	v_and_b32_e32 v73, 7, v71
	v_lshlrev_b32_e32 v70, 5, v73
	v_sub_u32_e32 v70, s3, v70
	s_waitcnt lgkmcnt(0)
	v_cmp_le_i32_e64 s[56:57], 0, v70
	v_cmp_le_i32_e64 s[58:59], 1, v70
	v_cmp_le_i32_e64 s[60:61], 2, v70
	v_cndmask_b32_e64 v148, 0, v148, s[56:57]
	v_cmp_le_i32_e64 s[56:57], 3, v70
	v_cndmask_b32_e64 v149, 0, v149, s[58:59]
	v_cmp_le_i32_e64 s[58:59], 4, v70
	v_cndmask_b32_e64 v150, 0, v150, s[60:61]
	v_cmp_le_i32_e64 s[60:61], 5, v70
	v_cndmask_b32_e64 v151, 0, v151, s[56:57]
	v_cmp_le_i32_e64 s[56:57], 6, v70
	v_cndmask_b32_e64 v152, 0, v152, s[58:59]
	v_cmp_le_i32_e64 s[58:59], 7, v70
	v_cndmask_b32_e64 v153, 0, v153, s[60:61]
	v_cmp_le_i32_e64 s[60:61], 8, v70
	v_cndmask_b32_e64 v154, 0, v154, s[56:57]
	v_cmp_le_i32_e64 s[56:57], 9, v70
	v_cndmask_b32_e64 v155, 0, v155, s[58:59]
	v_cmp_le_i32_e64 s[58:59], 10, v70
	v_cndmask_b32_e64 v156, 0, v156, s[60:61]
	v_cmp_le_i32_e64 s[60:61], 11, v70
	v_cndmask_b32_e64 v157, 0, v157, s[56:57]
	v_cmp_le_i32_e64 s[56:57], 12, v70
	v_cndmask_b32_e64 v158, 0, v158, s[58:59]
	v_cmp_le_i32_e64 s[58:59], 13, v70
	v_cndmask_b32_e64 v159, 0, v159, s[60:61]
	v_cmp_le_i32_e64 s[60:61], 14, v70
	v_cndmask_b32_e64 v160, 0, v160, s[56:57]
	v_cmp_le_i32_e64 s[56:57], 15, v70
	v_cndmask_b32_e64 v161, 0, v161, s[58:59]
	v_cmp_le_i32_e64 s[58:59], 16, v70
	v_cndmask_b32_e64 v162, 0, v162, s[60:61]
	v_cmp_le_i32_e64 s[60:61], 17, v70
	v_cndmask_b32_e64 v163, 0, v163, s[56:57]
	v_cmp_le_i32_e64 s[56:57], 18, v70
	v_cndmask_b32_e64 v164, 0, v164, s[58:59]
	v_cmp_le_i32_e64 s[58:59], 19, v70
	v_cndmask_b32_e64 v165, 0, v165, s[60:61]
	v_cmp_le_i32_e64 s[60:61], 20, v70
	v_cndmask_b32_e64 v166, 0, v166, s[56:57]
	v_cmp_le_i32_e64 s[56:57], 21, v70
	v_cndmask_b32_e64 v167, 0, v167, s[58:59]
	v_cmp_le_i32_e64 s[58:59], 22, v70
	v_cndmask_b32_e64 v168, 0, v168, s[60:61]
	v_cmp_le_i32_e64 s[60:61], 23, v70
	v_cndmask_b32_e64 v169, 0, v169, s[56:57]
	v_cmp_le_i32_e64 s[56:57], 24, v70
	v_cndmask_b32_e64 v170, 0, v170, s[58:59]
	v_cmp_le_i32_e64 s[58:59], 25, v70
	v_cndmask_b32_e64 v171, 0, v171, s[60:61]
	v_cmp_le_i32_e64 s[60:61], 26, v70
	v_cndmask_b32_e64 v172, 0, v172, s[56:57]
	v_cmp_le_i32_e64 s[56:57], 27, v70
	v_cndmask_b32_e64 v173, 0, v173, s[58:59]
	v_cmp_le_i32_e64 s[58:59], 28, v70
	v_cndmask_b32_e64 v174, 0, v174, s[60:61]
	v_cmp_le_i32_e64 s[60:61], 29, v70
	v_cndmask_b32_e64 v175, 0, v175, s[56:57]
	v_cmp_le_i32_e64 s[56:57], 30, v70
	v_cndmask_b32_e64 v176, 0, v176, s[58:59]
	v_cmp_le_i32_e64 s[58:59], 31, v70
	v_cndmask_b32_e64 v177, 0, v177, s[60:61]
	v_cndmask_b32_e64 v178, 0, v178, s[56:57]
	v_cndmask_b32_e64 v179, 0, v179, s[58:59]
	v_cmp_ne_u32_e64 s[56:57], 0, v73
	v_mov_b32_e32 v65, 0
	s_mov_b32 s24, 0x40000000
	v_cndmask_b32_e64 v148, 0, v148, s[56:57]
; __device__ __forceinline__ void select_blocks(const LAS float* sc, LAS unsigned* selm, int jhi, int f1, int f2, int lane) {
;     ...
;     unsigned prefix = 0u;
; #pragma unroll 1
;     ...
;         const unsigned c = prefix | (1u << bit); int cnt = 0;
; #pragma unroll
;         for (int rr = 0; rr < 4; ++rr) cnt += __popcll(__ballot(cand[rr] && key[rr] >= c));
;         if (cnt >= 13) prefix = c;
;     }
;     int cgt = 0; unsigned long long be[4];
; #pragma unroll
;     for (int rr = 0; rr < 4; ++rr) { cgt += __popcll(__ballot(cand[rr] && key[rr] > prefix)); be[rr] = __ballot(cand[rr] && key[rr] == prefix); }
.Lselx_loop:
	v_or_b32_e32 v66, s24, v65
	v_mov_b32_e32 v67, 0
	v_mov_b32_e32 v68, 0
	v_cmp_le_u32_e64 s[56:57], v66, v148
	v_cmp_le_u32_e64 s[58:59], v66, v149
	v_cmp_le_u32_e64 s[60:61], v66, v150
	v_addc_co_u32_e64 v67, s[62:63], 0, v67, s[56:57]
	v_cmp_le_u32_e64 s[56:57], v66, v151
	v_addc_co_u32_e64 v68, s[62:63], 0, v68, s[58:59]
	v_cmp_le_u32_e64 s[58:59], v66, v152
	v_addc_co_u32_e64 v67, s[62:63], 0, v67, s[60:61]
	v_cmp_le_u32_e64 s[60:61], v66, v153
	v_addc_co_u32_e64 v68, s[62:63], 0, v68, s[56:57]
	v_cmp_le_u32_e64 s[56:57], v66, v154
	v_addc_co_u32_e64 v67, s[62:63], 0, v67, s[58:59]
	v_cmp_le_u32_e64 s[58:59], v66, v155
	v_addc_co_u32_e64 v68, s[62:63], 0, v68, s[60:61]
	v_cmp_le_u32_e64 s[60:61], v66, v156
	v_addc_co_u32_e64 v67, s[62:63], 0, v67, s[56:57]
	v_cmp_le_u32_e64 s[56:57], v66, v157
	v_addc_co_u32_e64 v68, s[62:63], 0, v68, s[58:59]
	v_cmp_le_u32_e64 s[58:59], v66, v158
	v_addc_co_u32_e64 v67, s[62:63], 0, v67, s[60:61]
	v_cmp_le_u32_e64 s[60:61], v66, v159
	v_addc_co_u32_e64 v68, s[62:63], 0, v68, s[56:57]
	v_cmp_le_u32_e64 s[56:57], v66, v160
	v_addc_co_u32_e64 v67, s[62:63], 0, v67, s[58:59]
	v_cmp_le_u32_e64 s[58:59], v66, v161
	v_addc_co_u32_e64 v68, s[62:63], 0, v68, s[60:61]
	v_cmp_le_u32_e64 s[60:61], v66, v162
	v_addc_co_u32_e64 v67, s[62:63], 0, v67, s[56:57]
	v_cmp_le_u32_e64 s[56:57], v66, v163
	v_addc_co_u32_e64 v68, s[62:63], 0, v68, s[58:59]
	v_cmp_le_u32_e64 s[58:59], v66, v164
	v_addc_co_u32_e64 v67, s[62:63], 0, v67, s[60:61]
	v_cmp_le_u32_e64 s[60:61], v66, v165
	v_addc_co_u32_e64 v68, s[62:63], 0, v68, s[56:57]
	v_cmp_le_u32_e64 s[56:57], v66, v166
	v_addc_co_u32_e64 v67, s[62:63], 0, v67, s[58:59]
	v_cmp_le_u32_e64 s[58:59], v66, v167
	v_addc_co_u32_e64 v68, s[62:63], 0, v68, s[60:61]
	v_cmp_le_u32_e64 s[60:61], v66, v168
	v_addc_co_u32_e64 v67, s[62:63], 0, v67, s[56:57]
	v_cmp_le_u32_e64 s[56:57], v66, v169
	v_addc_co_u32_e64 v68, s[62:63], 0, v68, s[58:59]
	v_cmp_le_u32_e64 s[58:59], v66, v170
	v_addc_co_u32_e64 v67, s[62:63], 0, v67, s[60:61]
	v_cmp_le_u32_e64 s[60:61], v66, v171
	v_addc_co_u32_e64 v68, s[62:63], 0, v68, s[56:57]
	v_cmp_le_u32_e64 s[56:57], v66, v172
	v_addc_co_u32_e64 v67, s[62:63], 0, v67, s[58:59]
	v_cmp_le_u32_e64 s[58:59], v66, v173
	v_addc_co_u32_e64 v68, s[62:63], 0, v68, s[60:61]
	v_cmp_le_u32_e64 s[60:61], v66, v174
	v_addc_co_u32_e64 v67, s[62:63], 0, v67, s[56:57]
	v_cmp_le_u32_e64 s[56:57], v66, v175
	v_addc_co_u32_e64 v68, s[62:63], 0, v68, s[58:59]
	v_cmp_le_u32_e64 s[58:59], v66, v176
	v_addc_co_u32_e64 v67, s[62:63], 0, v67, s[60:61]
	v_cmp_le_u32_e64 s[60:61], v66, v177
	v_addc_co_u32_e64 v68, s[62:63], 0, v68, s[56:57]
	v_cmp_le_u32_e64 s[56:57], v66, v178
	v_addc_co_u32_e64 v67, s[62:63], 0, v67, s[58:59]
	v_cmp_le_u32_e64 s[58:59], v66, v179
	v_addc_co_u32_e64 v68, s[62:63], 0, v68, s[60:61]
	v_addc_co_u32_e64 v67, s[62:63], 0, v67, s[56:57]
	v_addc_co_u32_e64 v68, s[62:63], 0, v68, s[58:59]
	v_add_u32_e32 v67, v67, v68
	s_nop 1
	v_add_u32_dpp v69, v67, v67 quad_perm:[1,0,3,2] row_mask:0xf bank_mask:0xf
	s_nop 1
	v_add_u32_dpp v68, v69, v69 quad_perm:[2,3,0,1] row_mask:0xf bank_mask:0xf
	s_nop 1
	v_add_u32_dpp v67, v68, v68 row_half_mirror row_mask:0xf bank_mask:0xf
	v_cmp_lt_u32_e32 vcc, 12, v67
	s_lshr_b32 s24, s24, 1
	s_cmp_lg_u32 s24, 0
	v_cndmask_b32_e32 v65, v65, v66, vcc
	s_cbranch_scc1 .Lselx_loop
	v_mov_b32_e32 v74, 0
	v_mov_b32_e32 v75, 0
	v_cmp_lt_u32_e64 s[56:57], v65, v179
	v_cmp_eq_u32_e64 s[60:61], v65, v179
	v_cmp_lt_u32_e64 s[58:59], v65, v178
	v_cmp_eq_u32_e64 s[66:67], v65, v178
	v_addc_co_u32_e64 v74, s[62:63], v74, v74, s[56:57]
	v_addc_co_u32_e64 v75, s[62:63], v75, v75, s[60:61]
	v_cmp_lt_u32_e64 s[56:57], v65, v177
	v_cmp_eq_u32_e64 s[60:61], v65, v177
	v_addc_co_u32_e64 v74, s[62:63], v74, v74, s[58:59]
	v_addc_co_u32_e64 v75, s[62:63], v75, v75, s[66:67]
	v_cmp_lt_u32_e64 s[58:59], v65, v176
	v_cmp_eq_u32_e64 s[66:67], v65, v176
	v_addc_co_u32_e64 v74, s[62:63], v74, v74, s[56:57]
	v_addc_co_u32_e64 v75, s[62:63], v75, v75, s[60:61]
	v_cmp_lt_u32_e64 s[56:57], v65, v175
	v_cmp_eq_u32_e64 s[60:61], v65, v175
	v_addc_co_u32_e64 v74, s[62:63], v74, v74, s[58:59]
	v_addc_co_u32_e64 v75, s[62:63], v75, v75, s[66:67]
	v_cmp_lt_u32_e64 s[58:59], v65, v174
	v_cmp_eq_u32_e64 s[66:67], v65, v174
	v_addc_co_u32_e64 v74, s[62:63], v74, v74, s[56:57]
	v_addc_co_u32_e64 v75, s[62:63], v75, v75, s[60:61]
	v_cmp_lt_u32_e64 s[56:57], v65, v173
	v_cmp_eq_u32_e64 s[60:61], v65, v173
	v_addc_co_u32_e64 v74, s[62:63], v74, v74, s[58:59]
	v_addc_co_u32_e64 v75, s[62:63], v75, v75, s[66:67]
	v_cmp_lt_u32_e64 s[58:59], v65, v172
	v_cmp_eq_u32_e64 s[66:67], v65, v172
	v_addc_co_u32_e64 v74, s[62:63], v74, v74, s[56:57]
	v_addc_co_u32_e64 v75, s[62:63], v75, v75, s[60:61]
	v_cmp_lt_u32_e64 s[56:57], v65, v171
	v_cmp_eq_u32_e64 s[60:61], v65, v171
	v_addc_co_u32_e64 v74, s[62:63], v74, v74, s[58:59]
	v_addc_co_u32_e64 v75, s[62:63], v75, v75, s[66:67]
	v_cmp_lt_u32_e64 s[58:59], v65, v170
	v_cmp_eq_u32_e64 s[66:67], v65, v170
	v_addc_co_u32_e64 v74, s[62:63], v74, v74, s[56:57]
	v_addc_co_u32_e64 v75, s[62:63], v75, v75, s[60:61]
	v_cmp_lt_u32_e64 s[56:57], v65, v169
	v_cmp_eq_u32_e64 s[60:61], v65, v169
	v_addc_co_u32_e64 v74, s[62:63], v74, v74, s[58:59]
	v_addc_co_u32_e64 v75, s[62:63], v75, v75, s[66:67]
	v_cmp_lt_u32_e64 s[58:59], v65, v168
	v_cmp_eq_u32_e64 s[66:67], v65, v168
	v_addc_co_u32_e64 v74, s[62:63], v74, v74, s[56:57]
	v_addc_co_u32_e64 v75, s[62:63], v75, v75, s[60:61]
	v_cmp_lt_u32_e64 s[56:57], v65, v167
	v_cmp_eq_u32_e64 s[60:61], v65, v167
	v_addc_co_u32_e64 v74, s[62:63], v74, v74, s[58:59]
	v_addc_co_u32_e64 v75, s[62:63], v75, v75, s[66:67]
; #define WAVE_SYNC() do { __builtin_amdgcn_wave_barrier(); asm volatile("s_waitcnt lgkmcnt(0)" ::: "memory"); __builtin_amdgcn_wave_barrier(); } while (0)
; __device__ __forceinline__ void select_blocks(const LAS float* sc, LAS unsigned* selm, int jhi, int f1, int f2, int lane) {
;     ...
;     int cgt = 0; unsigned long long be[4];
; #pragma unroll
;     for (int rr = 0; rr < 4; ++rr) { cgt += __popcll(__ballot(cand[rr] && key[rr] > prefix)); be[rr] = __ballot(cand[rr] && key[rr] == prefix); }
;     const int need = 13 - cgt; const unsigned long long lt = (1ull << lane) - 1ull;
;     int before = 0;
; #pragma unroll
;     for (int rr = 0; rr < 4; ++rr) before += __popcll(be[rr] & lt);
;     unsigned nib = 0u;
; #pragma unroll
;     for (int rr = 0; rr < 4; ++rr) { const int j = 4 * lane + rr; const bool eq = cand[rr] && key[rr] == prefix;
;         const bool sel = (cand[rr] && key[rr] > prefix) || (eq && before < need) || (j == 0) || (j == f1) || (j == f2);
;         before += eq ? 1 : 0; nib |= sel ? (1u << rr) : 0u; }
;     if (lane < 8) selm[lane] = 0u;
;     WAVE_SYNC();
;     __hip_atomic_fetch_or(selm + (lane >> 3), nib << (4 * (lane & 7)), __ATOMIC_RELAXED, __HIP_MEMORY_SCOPE_WORKGROUP);
;     WAVE_SYNC();
; __device__ __forceinline__ void nsa_block_task(Ctx& C, int task, bf16* ONSA_OUT) {
;     ...
; #pragma unroll 1
;         for (int q = 0; q < 8; ++q) {
;             if (qb < 16) { if (lane < 8) SELM[q * 8 + lane] = (lane == 0) ? ((1u << (qb + 1)) - 1u) : 0u; }
;             else select_blocks(SC + q * 256, SELM + q * 8, qb - 2, qb, qb - 1, lane);
	v_cmp_lt_u32_e64 s[58:59], v65, v166
	v_cmp_eq_u32_e64 s[66:67], v65, v166
	v_addc_co_u32_e64 v74, s[62:63], v74, v74, s[56:57]
	v_addc_co_u32_e64 v75, s[62:63], v75, v75, s[60:61]
	v_cmp_lt_u32_e64 s[56:57], v65, v165
	v_cmp_eq_u32_e64 s[60:61], v65, v165
	v_addc_co_u32_e64 v74, s[62:63], v74, v74, s[58:59]
	v_addc_co_u32_e64 v75, s[62:63], v75, v75, s[66:67]
	v_cmp_lt_u32_e64 s[58:59], v65, v164
	v_cmp_eq_u32_e64 s[66:67], v65, v164
	v_addc_co_u32_e64 v74, s[62:63], v74, v74, s[56:57]
	v_addc_co_u32_e64 v75, s[62:63], v75, v75, s[60:61]
	v_cmp_lt_u32_e64 s[56:57], v65, v163
	v_cmp_eq_u32_e64 s[60:61], v65, v163
	v_addc_co_u32_e64 v74, s[62:63], v74, v74, s[58:59]
	v_addc_co_u32_e64 v75, s[62:63], v75, v75, s[66:67]
	v_cmp_lt_u32_e64 s[58:59], v65, v162
	v_cmp_eq_u32_e64 s[66:67], v65, v162
	v_addc_co_u32_e64 v74, s[62:63], v74, v74, s[56:57]
	v_addc_co_u32_e64 v75, s[62:63], v75, v75, s[60:61]
	v_cmp_lt_u32_e64 s[56:57], v65, v161
	v_cmp_eq_u32_e64 s[60:61], v65, v161
	v_addc_co_u32_e64 v74, s[62:63], v74, v74, s[58:59]
	v_addc_co_u32_e64 v75, s[62:63], v75, v75, s[66:67]
	v_cmp_lt_u32_e64 s[58:59], v65, v160
	v_cmp_eq_u32_e64 s[66:67], v65, v160
	v_addc_co_u32_e64 v74, s[62:63], v74, v74, s[56:57]
	v_addc_co_u32_e64 v75, s[62:63], v75, v75, s[60:61]
	v_cmp_lt_u32_e64 s[56:57], v65, v159
	v_cmp_eq_u32_e64 s[60:61], v65, v159
	v_addc_co_u32_e64 v74, s[62:63], v74, v74, s[58:59]
	v_addc_co_u32_e64 v75, s[62:63], v75, v75, s[66:67]
	v_cmp_lt_u32_e64 s[58:59], v65, v158
	v_cmp_eq_u32_e64 s[66:67], v65, v158
	v_addc_co_u32_e64 v74, s[62:63], v74, v74, s[56:57]
	v_addc_co_u32_e64 v75, s[62:63], v75, v75, s[60:61]
	v_cmp_lt_u32_e64 s[56:57], v65, v157
	v_cmp_eq_u32_e64 s[60:61], v65, v157
	v_addc_co_u32_e64 v74, s[62:63], v74, v74, s[58:59]
	v_addc_co_u32_e64 v75, s[62:63], v75, v75, s[66:67]
	v_cmp_lt_u32_e64 s[58:59], v65, v156
	v_cmp_eq_u32_e64 s[66:67], v65, v156
	v_addc_co_u32_e64 v74, s[62:63], v74, v74, s[56:57]
	v_addc_co_u32_e64 v75, s[62:63], v75, v75, s[60:61]
	v_cmp_lt_u32_e64 s[56:57], v65, v155
	v_cmp_eq_u32_e64 s[60:61], v65, v155
	v_addc_co_u32_e64 v74, s[62:63], v74, v74, s[58:59]
	v_addc_co_u32_e64 v75, s[62:63], v75, v75, s[66:67]
	v_cmp_lt_u32_e64 s[58:59], v65, v154
	v_cmp_eq_u32_e64 s[66:67], v65, v154
	v_addc_co_u32_e64 v74, s[62:63], v74, v74, s[56:57]
	v_addc_co_u32_e64 v75, s[62:63], v75, v75, s[60:61]
	v_cmp_lt_u32_e64 s[56:57], v65, v153
	v_cmp_eq_u32_e64 s[60:61], v65, v153
	v_addc_co_u32_e64 v74, s[62:63], v74, v74, s[58:59]
	v_addc_co_u32_e64 v75, s[62:63], v75, v75, s[66:67]
	v_cmp_lt_u32_e64 s[58:59], v65, v152
	v_cmp_eq_u32_e64 s[66:67], v65, v152
	v_addc_co_u32_e64 v74, s[62:63], v74, v74, s[56:57]
	v_addc_co_u32_e64 v75, s[62:63], v75, v75, s[60:61]
	v_cmp_lt_u32_e64 s[56:57], v65, v151
	v_cmp_eq_u32_e64 s[60:61], v65, v151
	v_addc_co_u32_e64 v74, s[62:63], v74, v74, s[58:59]
	v_addc_co_u32_e64 v75, s[62:63], v75, v75, s[66:67]
	v_cmp_lt_u32_e64 s[58:59], v65, v150
	v_cmp_eq_u32_e64 s[66:67], v65, v150
	v_addc_co_u32_e64 v74, s[62:63], v74, v74, s[56:57]
	v_addc_co_u32_e64 v75, s[62:63], v75, v75, s[60:61]
	v_cmp_lt_u32_e64 s[56:57], v65, v149
	v_cmp_eq_u32_e64 s[60:61], v65, v149
	v_addc_co_u32_e64 v74, s[62:63], v74, v74, s[58:59]
	v_addc_co_u32_e64 v75, s[62:63], v75, v75, s[66:67]
	v_cmp_lt_u32_e64 s[58:59], v65, v148
	v_cmp_eq_u32_e64 s[66:67], v65, v148
	v_addc_co_u32_e64 v74, s[62:63], v74, v74, s[56:57]
	v_addc_co_u32_e64 v75, s[62:63], v75, v75, s[60:61]
	v_addc_co_u32_e64 v74, s[62:63], v74, v74, s[58:59]
	v_addc_co_u32_e64 v75, s[62:63], v75, v75, s[66:67]
	v_min_i32_e32 v80, 31, v70
	v_lshlrev_b32_e64 v80, v80, 2
	v_add_u32_e32 v80, -1, v80
	v_cmp_gt_i32_e32 vcc, 0, v70
	v_cmp_eq_u32_e64 s[56:57], 0, v73
	s_nop 1
	v_cndmask_b32_e64 v80, v80, 0, vcc
	v_cndmask_b32_e64 v81, -1, -2, s[56:57]
	v_and_b32_e32 v76, v80, v81
	v_and_b32_e32 v75, v75, v76
	v_bcnt_u32_b32 v80, v74, 0
	s_nop 1
	v_add_u32_dpp v81, v80, v80 quad_perm:[1,0,3,2] row_mask:0xf bank_mask:0xf
	s_nop 1
	v_add_u32_dpp v80, v81, v81 quad_perm:[2,3,0,1] row_mask:0xf bank_mask:0xf
	s_nop 1
	v_add_u32_dpp v81, v80, v80 row_half_mirror row_mask:0xf bank_mask:0xf
	v_sub_u32_e32 v77, 13, v81
	v_bcnt_u32_b32 v80, v75, 0
	v_mov_b32_e32 v78, v80
	v_mov_b32_e32 v81, 0
	v_cmp_le_u32_e64 s[56:57], 1, v73
	s_nop 0
	v_mov_b32_dpp v81, v78 row_shr:1 row_mask:0xf bank_mask:0xf
	s_nop 0
	v_cndmask_b32_e64 v81, 0, v81, s[56:57]
	v_add_u32_e32 v78, v78, v81
	v_mov_b32_e32 v81, 0
	v_cmp_le_u32_e64 s[56:57], 2, v73
	s_nop 0
	v_mov_b32_dpp v81, v78 row_shr:2 row_mask:0xf bank_mask:0xf
	s_nop 0
	v_cndmask_b32_e64 v81, 0, v81, s[56:57]
	v_add_u32_e32 v78, v78, v81
	v_mov_b32_e32 v81, 0
	v_cmp_le_u32_e64 s[56:57], 4, v73
	s_nop 0
	v_mov_b32_dpp v81, v78 row_shr:4 row_mask:0xf bank_mask:0xf
	s_nop 0
	v_cndmask_b32_e64 v81, 0, v81, s[56:57]
	v_add_u32_e32 v78, v78, v81
	v_sub_u32_e32 v78, v78, v80
	v_sub_u32_e32 v77, v77, v78
	v_mov_b32_e32 v79, 0
.Lselx_eq:
	v_cmp_lt_i32_e64 s[56:57], 0, v77
	v_cmp_ne_u32_e64 s[58:59], 0, v75
	s_and_b64 vcc, s[56:57], s[58:59]
	s_cbranch_vccz .Lselx_eqdone
	v_sub_u32_e32 v80, 0, v75
	v_and_b32_e32 v80, v75, v80
	v_cndmask_b32_e32 v80, 0, v80, vcc
	v_cndmask_b32_e64 v81, 0, 1, vcc
	v_or_b32_e32 v79, v79, v80
	v_xor_b32_e32 v75, v75, v80
	v_sub_u32_e32 v77, v77, v81
	s_branch .Lselx_eq
.Lselx_eqdone:
	v_cmp_eq_u32_e32 vcc, 0, v73
	s_lshr_b32 s3, s94, 5
	s_and_b32 s24, s94, 31
	s_lshl_b32 s24, 1, s24
	v_cndmask_b32_e64 v82, 0, 1, vcc
	v_mov_b32_e32 v80, s24
	v_cmp_eq_u32_e32 vcc, s3, v73
	s_add_i32 s25, s94, -1
	s_lshr_b32 s3, s25, 5
	s_and_b32 s24, s25, 31
	s_lshl_b32 s24, 1, s24
	v_cndmask_b32_e32 v80, 0, v80, vcc
	v_mov_b32_e32 v81, s24
	v_cmp_eq_u32_e32 vcc, s3, v73
	v_or_b32_e32 v82, v82, v80
	v_lshl_add_u32 v83, v71, 2, s76
	v_cndmask_b32_e32 v81, 0, v81, vcc
	v_or3_b32 v80, v74, v79, v82
	v_or_b32_e32 v80, v80, v81
	ds_write_b32 v83, v80
	s_waitcnt lgkmcnt(0)
	s_branch .LBB0_1204
.Lselx_skip:
	s_branch .LBB0_1155
.LBB0_1153:
	s_or_b64 exec, exec, s[24:25]

; #define LAS __attribute__((address_space(3)))
; __device__ __forceinline__ int launder_v(int x) { asm volatile("" : "+v"(x)); return x; }
; #define WAVE_SYNC() do { __builtin_amdgcn_wave_barrier(); asm volatile("s_waitcnt lgkmcnt(0)" ::: "memory"); __builtin_amdgcn_wave_barrier(); } while (0)
; __device__ __forceinline__ void nsa_block_task(Ctx& C, int task, bf16* ONSA_OUT) {
;     ...
; #pragma unroll 1
;         for (int q = 0; q < 8; ++q) {
;             if (qb < 16) { if (lane < 8) SELM[q * 8 + lane] = (lane == 0) ? ((1u << (qb + 1)) - 1u) : 0u; }
;             else select_blocks(SC + q * 256, SELM + q * 8, qb - 2, qb, qb - 1, lane);
;         }
;     }
;     WAVE_SYNC();
;     LAS unsigned* ANYM = (LAS unsigned*)(C.lds + 135168 + w * 64);
;     { const int la = launder_v(lane); if (la < 16) { const int cgx = la >> 3, w8 = la & 7; ANYM[la] = SELM[(4 * cgx + 0) * 8 + w8] | SELM[(4 * cgx + 1) * 8 + w8] | SELM[(4 * cgx + 2) * 8 + w8] | SELM[(4 * cgx + 3) * 8 + w8]; } }
;     WAVE_SYNC();
.LBB0_1155:
	s_mov_b64 s[24:25], -1
.LBB0_1193:
	s_and_b64 vcc, exec, s[24:25]
	s_cbranch_vccz .LBB0_1154
	s_and_saveexec_b64 s[24:25], s[12:13]
	s_cbranch_execz .LBB0_1153
	v_add_u32_e32 v54, s76, v193
	v_lshl_add_u32 v54, s50, 5, v54
	ds_write_b32 v54, v53
	s_branch .LBB0_1153
.LBB0_1204:
	s_waitcnt lgkmcnt(0)
	v_mov_b32_e32 v0, v190
	s_nop 0
	v_cmp_gt_i32_e32 vcc, 16, v0
	s_and_saveexec_b64 s[16:17], vcc
	s_cbranch_execz .LBB0_1206
	v_lshlrev_b32_e32 v2, 4, v0
	v_lshlrev_b32_e32 v0, 2, v0
	v_and_b32_e32 v52, 0xffffff80, v2
	v_and_b32_e32 v53, 28, v0
	v_add3_u32 v54, s76, v52, v53
	v_or_b32_e32 v52, v52, v53
	ds_read2_b32 v[2:3], v54 offset1:8
	v_add_u32_e32 v52, s76, v52
	ds_read_b32 v53, v54 offset:64
	ds_read_b32 v52, v52 offset:96
	v_add_u32_e32 v0, s77, v0
	s_waitcnt lgkmcnt(2)
	v_or_b32_e32 v2, v3, v2
	s_waitcnt lgkmcnt(0)
	v_or3_b32 v2, v2, v53, v52
	ds_write_b32 v0, v2
